# XCD-local + block-synchronous item queues also for q4 filler (dil+win) and phaseX (cmp+win)
# speedup vs baseline: 1.1493x; 1.0062x over previous
;   unsigned char* blut = (unsigned char*)lds; float* tbl = (float*)(lds + 4096);
;   build_lut(blut, tbl, p.in[I_RELB]);
;   unsigned* ctr = (unsigned*)(p.ws + OFF_MISC) + layer * 2 + rep * 8;
.LBB0_140:
	s_or_b64 exec, exec, s[8:9]
	v_readlane_b32 s10, v254, 1
	s_and_b32 s10, s10, 7
	s_lshl_b32 s101, s10, 1
	s_mul_i32 s100, s10, 6
	s_addk_i32 s100, 0x800
	s_lshl_b32 s10, s10, 2
	s_lshl_b32 s8, s47, 5
	s_add_u32 s10, s10, s8
	s_add_u32 s10, s10, 0x65c1880
	s_add_u32 s40, s34, s10
	s_addc_u32 s41, s35, 0
	s_mov_b64 s[70:71], 0
	s_waitcnt vmcnt(0) lgkmcnt(0)
	s_barrier
	s_branch .LBB0_144

; #define TIDX get_tid_()
; DI void nsa_win_item(const Params& p, int b, int head, int qb, const unsigned char* blut, const float* tbl) {
;   const int lane = TIDX & 63, r = lane & 31, h = lane >> 5;
;   const int g = head / 3, bg = b * 2 + g;
;   const int t = qb * 32 + r;
;   const float* tblh = tbl + head * 32;
;   bf16x8 qf[4];
;   load_q(qf, (const bf16_t*)(p.ws + OFF_QN) + (size_t)(b * 4096 + t) * 384 + head * 64 + 8 * h);
;   const float g2 = ((const float*)(p.ws + OFF_GATES))[(size_t)(b * 4096 + t) * 18 + head * 3 + 2];
;   f32x16 y0, y1;
; #pragma unroll
;   for (int i = 0; i < 16; ++i) { y0[i] = 0.f; y1[i] = 0.f; }
;   {
;     const bf16_t* K = (const bf16_t*)(p.ws + OFF_KWIN) + (size_t)bg * 4096 * 64;
;     const bf16_t* Vt = (const bf16_t*)(p.ws + OFF_VWINT) + (size_t)bg * 64 * 4096;
;     AttnSt st; attn_init(st);
;     const int k0 = qb >= 16 ? qb - 16 : 0;
;     attn_loop(st, qf, k0, qb, 32,
;     ...
;   build_lut(blut, tbl, p.in[I_RELB]);
;   unsigned* ctr = (unsigned*)(p.ws + OFF_MISC) + layer * 2 + rep * 8;
;   for (;;) {
;     const int item = wave_fetch(ctr);
;     if (item >= 2048 + 32 * 48) break;
;     if (item < 2048) nsa_cmp_item(p, item, blut, tbl, (float*)(lds + 8192) + (TIDX >> 6) * (32 * 65));
;     else { const int it2 = item - 2048, qb = 31 - it2 / 48, sub = it2 % 48; nsa_win_item(p, sub / 6, sub % 6, qb, blut, tbl); }
.LBB0_144:
	s_barrier
	v_mov_b32_e32 v0, 0x1900
	v_cmp_eq_u32_e32 vcc, 0, v129
	s_and_saveexec_b64 s[8:9], vcc
	s_cbranch_execz .Lf6_skip
	v_mov_b32_e32 v1, 8
	global_atomic_add v1, v131, v1, s[40:41] sc0
	s_waitcnt vmcnt(0)
	ds_write_b32 v0, v1
	s_waitcnt lgkmcnt(0)
.Lf6_skip:
	s_or_b64 exec, exec, s[8:9]
	s_barrier
	ds_read_b32 v0, v0
	v_lshrrev_b32_e32 v1, 6, v129
	s_waitcnt lgkmcnt(0)
	v_add_u32_e32 v0, v0, v1
	s_nop 1
	v_readfirstlane_b32 s10, v0
	s_cmp_lt_u32 s10, 0x1c0
	s_cbranch_scc1 .Lf6_in
	s_movk_i32 s10, 0x7fff
	s_branch .Lf6_done
.Lf6_in:
	s_and_b32 s11, s10, 7
	s_bfe_u32 s14, s10, 0x10003
	s_cmp_lt_u32 s10, 0x100
	s_cbranch_scc0 .Lf6_win
	s_lshr_b32 s10, s10, 4
	s_lshl_b32 s10, s10, 3
	s_add_u32 s10, s10, s11
	s_lshl_b32 s10, s10, 4
	s_add_u32 s10, s10, s14
	s_add_u32 s10, s10, s101
	s_branch .Lf6_done
.Lf6_win:
	s_sub_u32 s10, s10, 0x100
	s_lshr_b32 s10, s10, 4
	s_lshl_b32 s10, s10, 3
	s_add_u32 s10, s10, s11
	s_mul_i32 s11, s10, 0x5556
	s_lshr_b32 s11, s11, 16
	s_mul_i32 s11, s11, 45
	s_add_u32 s10, s10, s11
	s_mul_i32 s14, s14, 3
	s_add_u32 s10, s10, s14
	s_add_u32 s10, s10, s100
.Lf6_done:
	v_mov_b32_e32 v2, s10
	s_movk_i32 s8, 0xe00
	s_waitcnt lgkmcnt(0)
	v_cmp_gt_i32_e32 vcc, s8, v2
	s_mov_b64 s[8:9], -1
	s_and_saveexec_b64 s[68:69], vcc
	s_cbranch_execz .LBB0_143
	s_movk_i32 s8, 0x7ff
	v_cmp_lt_i32_e32 vcc, s8, v2
	s_and_saveexec_b64 s[8:9], vcc
	s_xor_b64 s[8:9], exec, s[8:9]
	s_cbranch_execz .LBB0_158
	v_add_u16_e32 v0, 0xf800, v2
	v_mul_u32_u24_e32 v1, 0xaaab, v0
	v_lshrrev_b32_e32 v32, 21, v1
	v_mul_lo_u16_e32 v1, 48, v32
	v_sub_u16_e32 v0, v0, v1
	s_movk_i32 s10, 0xab
	v_mul_lo_u16_sdwa v1, v0, s10 dst_sel:DWORD dst_unused:UNUSED_PAD src0_sel:BYTE_0 src1_sel:DWORD
	v_lshrrev_b16_e32 v4, 10, v1
	v_mul_lo_u16_e32 v1, 6, v4
	v_sub_u16_e32 v33, v0, v1
	v_mov_b32_e32 v0, v129
	v_sub_u32_sdwa v138, v200, v32 dst_sel:DWORD dst_unused:UNUSED_PAD src0_sel:DWORD src1_sel:WORD_0
	v_readlane_b32 s10, v253, 13
	v_and_b32_e32 v34, 31, v0
	v_bfe_u32 v35, v0, 5, 1
	v_lshlrev_b32_e32 v0, 5, v138
	v_lshlrev_b32_e32 v1, 12, v4
	v_readlane_b32 s11, v253, 14
	v_or3_b32 v113, v34, v0, v1
	v_lshlrev_b32_sdwa v130, v202, v33 dst_sel:DWORD dst_unused:UNUSED_PAD src0_sel:DWORD src1_sel:BYTE_0
	v_mov_b64_e32 v[0:1], s[10:11]
	s_movk_i32 s10, 0x300
	v_mad_u64_u32 v[0:1], s[10:11], v113, s10, v[0:1]
	v_lshl_add_u64 v[0:1], v[0:1], 0, v[130:131]
	v_lshlrev_b32_e32 v2, 4, v35
	v_mov_b32_e32 v3, v131
	v_cmp_gt_u16_sdwa vcc, v33, v204 src0_sel:BYTE_0 src1_sel:DWORD
	v_lshl_add_u64 v[8:9], v[0:1], 0, v[2:3]
	v_readlane_b32 s10, v253, 31
	v_cndmask_b32_e32 v0, 0, v205, vcc
	v_add_u32_e32 v139, 0, v130
	v_lshl_or_b32 v130, v4, 20, v0
	v_readlane_b32 s11, v253, 32
	v_sub_u32_sdwa v36, v206, v32 clamp dst_sel:DWORD dst_unused:UNUSED_PAD src0_sel:DWORD src1_sel:WORD_0
	v_lshlrev_b32_e32 v2, 3, v34
	v_lshl_add_u64 v[24:25], s[10:11], 0, v[130:131]
	v_readlane_b32 s10, v253, 33
	v_readlane_b32 s11, v253, 34
	v_lshl_or_b32 v28, v35, 8, v2
	v_lshlrev_b32_e32 v30, 1, v28
	v_lshl_add_u64 v[26:27], s[10:11], 0, v[130:131]
	v_lshlrev_b32_e32 v130, 12, v36
	v_lshl_add_u64 v[0:1], v[24:25], 0, v[130:131]
	v_mov_b32_e32 v31, v131
	v_lshl_add_u64 v[10:11], v[0:1], 0, v[30:31]
	global_load_dwordx4 v[0:3], v[10:11], off
	global_load_dwordx4 v[64:67], v[8:9], off
	v_readlane_b32 s10, v253, 29
	v_readlane_b32 s11, v253, 30
	v_mul_u32_u24_sdwa v6, v33, v203 dst_sel:DWORD dst_unused:UNUSED_PAD src0_sel:BYTE_0 src1_sel:DWORD
	v_lshlrev_b32_e32 v14, 2, v6
	v_mov_b64_e32 v[4:5], s[10:11]
	s_movk_i32 s10, 0x48
	v_mad_u64_u32 v[12:13], s[10:11], v113, s10, v[4:5]
	global_load_dwordx4 v[4:7], v[10:11], off offset:1024
	v_mov_b32_e32 v15, v131
	v_lshl_add_u64 v[12:13], v[12:13], 0, v[14:15]
	global_load_dword v140, v[12:13], off
	global_load_dwordx4 v[68:71], v[8:9], off offset:32
	global_load_dwordx4 v[72:75], v[8:9], off offset:64
	global_load_dwordx4 v[76:79], v[8:9], off offset:96
	global_load_dwordx4 v[16:19], v[10:11], off offset:2048
	global_load_dwordx4 v[20:23], v[10:11], off offset:3072
	v_add_u32_e32 v8, 1, v36
	v_cmp_lt_u32_e32 vcc, v36, v138
	v_mov_b32_e32 v9, v131
	v_mov_b32_e32 v29, v131
	v_cndmask_b32_e32 v8, v138, v8, vcc
	v_lshlrev_b32_e32 v8, 12, v8
	v_lshl_add_u64 v[8:9], v[24:25], 0, v[8:9]
	v_lshl_add_u64 v[10:11], v[26:27], 0, v[130:131]
	v_lshl_add_u64 v[8:9], v[8:9], 0, v[30:31]
	v_lshl_add_u64 v[10:11], v[10:11], 0, v[28:29]
	global_load_dwordx4 v[88:91], v[8:9], off offset:2048
	global_load_dwordx4 v[80:83], v[8:9], off offset:1024
	global_load_dwordx4 v[92:95], v[8:9], off
	global_load_dwordx2 v[86:87], v[10:11], off offset:3584
	global_load_dwordx2 v[84:85], v[10:11], off offset:3072
	global_load_dwordx2 v[102:103], v[10:11], off offset:2560
	global_load_dwordx2 v[100:101], v[10:11], off offset:2048
	global_load_dwordx2 v[106:107], v[10:11], off offset:1536
	global_load_dwordx2 v[104:105], v[10:11], off offset:1024
	global_load_dwordx2 v[110:111], v[10:11], off offset:512
	global_load_dwordx4 v[96:99], v[8:9], off offset:3072
	global_load_dwordx2 v[108:109], v[10:11], off
	s_mov_b32 s53, s52
	v_lshlrev_b32_e32 v141, 2, v35
	s_mov_b32 s54, s52
	s_mov_b32 s55, s52
	s_mov_b32 s56, s52
	s_mov_b32 s57, s52
	s_mov_b32 s58, s52
	s_mov_b32 s59, s52
	s_mov_b32 s60, s52
	s_mov_b32 s61, s52
	s_mov_b32 s62, s52
	s_mov_b32 s63, s52
	s_mov_b32 s64, s52
	s_mov_b32 s65, s52
	s_mov_b32 s66, s52
	s_mov_b32 s67, s52
	v_lshl_add_u64 v[114:115], v[26:27], 0, v[28:29]
	v_lshl_add_u64 v[116:117], v[24:25], 0, v[30:31]
	v_lshlrev_b32_sdwa v112, v201, v33 dst_sel:DWORD dst_unused:UNUSED_PAD src0_sel:DWORD src1_sel:BYTE_0
	v_mov_b32_e32 v145, 0
	v_mov_b32_e32 v146, 0xff800000
	s_mov_b64 s[10:11], 0
	s_waitcnt vmcnt(19)
	v_mfma_f32_32x32x16_bf16 v[48:63], v[0:3], v[64:67], 0
	s_waitcnt vmcnt(16)
	v_mfma_f32_32x32x16_bf16 v[48:63], v[4:7], v[68:71], v[48:63]
	v_mov_b64_e32 v[0:1], s[52:53]
	v_mov_b64_e32 v[14:15], s[66:67]
	v_mov_b64_e32 v[2:3], s[54:55]
	v_mov_b64_e32 v[4:5], s[56:57]
	v_mov_b64_e32 v[6:7], s[58:59]
	v_mov_b64_e32 v[8:9], s[60:61]
	v_mov_b64_e32 v[10:11], s[62:63]
	s_waitcnt vmcnt(13)
	v_mfma_f32_32x32x16_bf16 v[48:63], v[16:19], v[72:75], v[48:63]
	v_min_u32_sdwa v16, v32, v206 dst_sel:DWORD dst_unused:UNUSED_PAD src0_sel:WORD_0 src1_sel:DWORD
	v_lshl_or_b32 v17, v16, 5, v34
	v_sub_u32_e32 v17, v17, v141
	v_lshlrev_b32_sdwa v18, v207, v32 dst_sel:DWORD dst_unused:UNUSED_PAD src0_sel:DWORD src1_sel:WORD_0
	v_sub_u32_e32 v17, v17, v18
	v_mov_b64_e32 v[12:13], s[64:65]
	v_add_u32_e32 v142, 0x1e5, v17
	s_waitcnt vmcnt(12)
	v_mfma_f32_32x32x16_bf16 v[48:63], v[20:23], v[76:79], v[48:63]
	v_sub_u32_e32 v143, 17, v16
	v_mov_b64_e32 v[30:31], v[14:15]
	v_mov_b64_e32 v[28:29], v[12:13]
	v_mov_b64_e32 v[26:27], v[10:11]
	v_mov_b64_e32 v[24:25], v[8:9]
	v_mov_b64_e32 v[22:23], v[6:7]
	v_mov_b64_e32 v[20:21], v[4:5]
	v_mov_b64_e32 v[18:19], v[2:3]
	v_mov_b64_e32 v[16:17], v[0:1]
	s_branch .LBB0_153

; DI void filler_items(const Params& p, int layer, char* lds, int which) {
;   __syncthreads();
;   unsigned char* blut = (unsigned char*)lds; float* tbl = (float*)(lds + 4096);
;   build_lut(blut, tbl, p.in[I_RELB]);
;   unsigned* ctr = (unsigned*)(p.ws + OFF_MISC) + 16 + layer * 2 + which;
.LBB0_1020:
	s_or_b64 exec, exec, s[8:9]
	v_readlane_b32 s10, v254, 1
	s_and_b32 s10, s10, 7
	s_lshl_b32 s101, s10, 1
	s_mul_i32 s100, s10, 6
	s_addk_i32 s100, 0x800
	s_lshl_b32 s10, s10, 2
	s_lshl_b32 s8, s47, 5
	s_add_u32 s10, s10, s8
	s_add_u32 s10, s10, 0x65c1840
	s_add_u32 s36, s34, s10
	s_addc_u32 s37, s35, 0
	s_mov_b64 s[10:11], 0
	s_waitcnt lgkmcnt(0)
	s_barrier
	s_branch .LBB0_1025

; #define TIDX get_tid_()
; DI void nsa_win_item(const Params& p, int b, int head, int qb, const unsigned char* blut, const float* tbl) {
;   const int lane = TIDX & 63, r = lane & 31, h = lane >> 5;
;   const int g = head / 3, bg = b * 2 + g;
;   const int t = qb * 32 + r;
;   const float* tblh = tbl + head * 32;
;   bf16x8 qf[4];
;   load_q(qf, (const bf16_t*)(p.ws + OFF_QN) + (size_t)(b * 4096 + t) * 384 + head * 64 + 8 * h);
;   const float g2 = ((const float*)(p.ws + OFF_GATES))[(size_t)(b * 4096 + t) * 18 + head * 3 + 2];
;   f32x16 y0, y1;
; #pragma unroll
;   for (int i = 0; i < 16; ++i) { y0[i] = 0.f; y1[i] = 0.f; }
;   {
;     const bf16_t* K = (const bf16_t*)(p.ws + OFF_KWIN) + (size_t)bg * 4096 * 64;
;     const bf16_t* Vt = (const bf16_t*)(p.ws + OFF_VWINT) + (size_t)bg * 64 * 4096;
;     AttnSt st; attn_init(st);
;     const int k0 = qb >= 16 ? qb - 16 : 0;
;     attn_loop(st, qf, k0, qb, 32,
; DI void filler_items(const Params& p, int layer, char* lds, int which) {
;     ...
;   for (;;) {
;     const int item = wave_fetch(ctr);
;     if (which == 0) {
;       if (item >= 128 * 16 + 96 * 48) break;
;       if (item < 128 * 16) { const int qb = 127 - item / 16, sub = item % 16; dil_item(p, sub >> 1, sub & 1, qb, blut, tbl); }
;       else { const int it2 = item - 128 * 16, qb = 127 - it2 / 48, sub = it2 % 48; nsa_win_item(p, sub / 6, sub % 6, qb, blut, tbl); }
.LBB0_1025:
	s_barrier
	v_mov_b32_e32 v0, 0x1900
	v_cmp_eq_u32_e32 vcc, 0, v129
	s_and_saveexec_b64 s[8:9], vcc
	s_cbranch_execz .Lf4_skip
	v_mov_b32_e32 v1, 8
	global_atomic_add v1, v131, v1, s[36:37] sc0
	s_waitcnt vmcnt(0)
	ds_write_b32 v0, v1
	s_waitcnt lgkmcnt(0)
.Lf4_skip:
	s_or_b64 exec, exec, s[8:9]
	s_barrier
	ds_read_b32 v0, v0
	v_lshrrev_b32_e32 v1, 6, v129
	s_waitcnt lgkmcnt(0)
	v_add_u32_e32 v0, v0, v1
	s_nop 1
	v_readfirstlane_b32 s14, v0
	s_cmp_lt_u32 s14, 0x340
	s_cbranch_scc1 .Lf4_in
	s_movk_i32 s14, 0x7fff
	s_branch .Lf4_done
.Lf4_in:
	s_and_b32 s15, s14, 7
	s_bfe_u32 s54, s14, 0x10003
	s_cmp_lt_u32 s14, 0x100
	s_cbranch_scc0 .Lf4_win
	s_lshr_b32 s14, s14, 4
	s_lshl_b32 s14, s14, 3
	s_add_u32 s14, s14, s15
	s_lshl_b32 s14, s14, 4
	s_add_u32 s14, s14, s54
	s_add_u32 s14, s14, s101
	s_branch .Lf4_done
.Lf4_win:
	s_sub_u32 s14, s14, 0x100
	s_lshr_b32 s14, s14, 4
	s_lshl_b32 s14, s14, 3
	s_add_u32 s14, s14, s15
	s_mul_i32 s15, s14, 0x5556
	s_lshr_b32 s15, s15, 16
	s_mul_i32 s15, s15, 45
	s_add_u32 s14, s14, s15
	s_mul_i32 s54, s54, 3
	s_add_u32 s14, s14, s54
	s_add_u32 s14, s14, s100
.Lf4_done:
	v_mov_b32_e32 v4, s14
	s_movk_i32 s8, 0x1a00
	s_waitcnt lgkmcnt(0)
	v_cmp_gt_i32_e32 vcc, s8, v4
	s_mov_b64 s[8:9], -1
	s_and_saveexec_b64 s[14:15], vcc
	s_cbranch_execz .LBB0_1024
	s_movk_i32 s8, 0x7ff
	v_cmp_lt_i32_e32 vcc, s8, v4
	s_and_saveexec_b64 s[8:9], vcc
	s_xor_b64 s[8:9], exec, s[8:9]
	s_cbranch_execz .LBB0_1039
	v_add_u16_e32 v0, 0xf800, v4
	v_mul_u32_u24_e32 v1, 0xaaab, v0
	v_lshrrev_b32_e32 v30, 21, v1
	s_movk_i32 s23, 0x7f
	v_mul_lo_u16_e32 v1, 48, v30
	v_sub_u32_sdwa v138, s23, v30 dst_sel:DWORD dst_unused:UNUSED_PAD src0_sel:DWORD src1_sel:WORD_0
	v_sub_u16_e32 v0, v0, v1
	s_movk_i32 s23, 0xab
	v_mul_lo_u16_sdwa v1, v0, s23 dst_sel:DWORD dst_unused:UNUSED_PAD src0_sel:BYTE_0 src1_sel:DWORD
	v_lshrrev_b16_e32 v2, 10, v1
	v_mul_lo_u16_e32 v1, 6, v2
	v_sub_u16_e32 v31, v0, v1
	v_mov_b32_e32 v0, v129
	v_readlane_b32 s24, v253, 13
	v_and_b32_e32 v32, 31, v0
	v_bfe_u32 v33, v0, 5, 1
	v_lshlrev_b32_e32 v0, 5, v138
	v_lshlrev_b32_e32 v1, 12, v2
	v_readlane_b32 s25, v253, 14
	v_or3_b32 v113, v32, v0, v1
	s_movk_i32 s23, 0x300
	v_mov_b64_e32 v[0:1], s[24:25]
	v_mad_u64_u32 v[0:1], s[26:27], v113, s23, v[0:1]
	v_lshlrev_b32_sdwa v130, v202, v31 dst_sel:DWORD dst_unused:UNUSED_PAD src0_sel:DWORD src1_sel:BYTE_0
	v_cmp_gt_u16_sdwa vcc, v31, v204 src0_sel:BYTE_0 src1_sel:DWORD
	v_lshl_add_u64 v[4:5], v[0:1], 0, v[130:131]
	v_readlane_b32 s24, v253, 31
	v_cndmask_b32_e32 v0, 0, v205, vcc
	v_add_u32_e32 v139, 0, v130
	v_lshl_or_b32 v130, v2, 20, v0
	v_readlane_b32 s25, v253, 32
	s_movk_i32 s23, 0x6f
	v_sub_u32_sdwa v0, s23, v30 dst_sel:DWORD dst_unused:UNUSED_PAD src0_sel:DWORD src1_sel:WORD_0
	v_lshl_add_u64 v[20:21], s[24:25], 0, v[130:131]
	v_readlane_b32 s24, v253, 33
	v_readlane_b32 s25, v253, 34
	v_lshlrev_b32_e32 v2, 3, v32
	v_lshl_or_b32 v24, v33, 8, v2
	v_lshl_add_u64 v[22:23], s[24:25], 0, v[130:131]
	v_lshlrev_b32_e32 v130, 12, v0
	v_lshl_add_u64 v[0:1], v[20:21], 0, v[130:131]
	v_lshlrev_b32_e32 v26, 1, v24
	v_mov_b32_e32 v27, v131
	v_lshl_add_u64 v[12:13], v[0:1], 0, v[26:27]
	global_load_dwordx4 v[0:3], v[12:13], off
	v_lshlrev_b32_e32 v6, 4, v33
	v_mov_b32_e32 v7, v131
	v_lshl_add_u64 v[14:15], v[4:5], 0, v[6:7]
	global_load_dwordx4 v[64:67], v[14:15], off
	global_load_dwordx4 v[68:71], v[14:15], off offset:32
	global_load_dwordx4 v[4:7], v[12:13], off offset:1024
	v_readlane_b32 s24, v253, 29
	v_readlane_b32 s25, v253, 30
	v_lshlrev_b32_sdwa v10, v209, v30 dst_sel:DWORD dst_unused:UNUSED_PAD src0_sel:DWORD src1_sel:WORD_0
	v_sub_u32_e32 v16, 0x70000, v10
	v_mov_b64_e32 v[8:9], s[24:25]
	v_mul_u32_u24_sdwa v10, v31, v203 dst_sel:DWORD dst_unused:UNUSED_PAD src0_sel:BYTE_0 src1_sel:DWORD
	s_movk_i32 s23, 0x48
	v_mov_b32_e32 v11, v131
	v_mad_u64_u32 v[8:9], s[26:27], v113, s23, v[8:9]
	v_lshlrev_b32_e32 v10, 2, v10
	v_lshl_add_u64 v[18:19], v[8:9], 0, v[10:11]
	global_load_dwordx4 v[8:11], v[12:13], off offset:2048
	global_load_dwordx4 v[72:75], v[14:15], off offset:64
	global_load_dwordx4 v[76:79], v[14:15], off offset:96
	v_mov_b32_e32 v17, v131
	v_lshl_add_u64 v[14:15], v[20:21], 0, v[16:17]
	v_mov_b32_e32 v25, v131
	v_lshl_add_u64 v[16:17], v[22:23], 0, v[130:131]
	v_lshl_add_u64 v[14:15], v[14:15], 0, v[26:27]
	v_lshl_add_u64 v[28:29], v[16:17], 0, v[24:25]
	global_load_dword v140, v[18:19], off
	s_nop 0
	global_load_dwordx4 v[16:19], v[12:13], off offset:3072
	global_load_dwordx4 v[88:91], v[14:15], off offset:2048
	global_load_dwordx4 v[84:87], v[14:15], off offset:1024
	global_load_dwordx4 v[92:95], v[14:15], off
	global_load_dwordx2 v[82:83], v[28:29], off offset:3584
	global_load_dwordx2 v[80:81], v[28:29], off offset:3072
	global_load_dwordx2 v[98:99], v[28:29], off offset:2560
	global_load_dwordx2 v[96:97], v[28:29], off offset:2048
	global_load_dwordx2 v[106:107], v[28:29], off offset:1536
	global_load_dwordx2 v[104:105], v[28:29], off offset:1024
	global_load_dwordx2 v[110:111], v[28:29], off offset:512
	global_load_dwordx4 v[100:103], v[14:15], off offset:3072
	global_load_dwordx2 v[108:109], v[28:29], off
	s_mov_b32 s56, 0
	s_mov_b32 s57, s56
	s_mov_b32 s58, s56
	s_mov_b32 s59, s56
	s_mov_b32 s60, s56
	s_mov_b32 s61, s56
	s_mov_b32 s62, s56
	s_mov_b32 s63, s56
	s_mov_b32 s64, s56
	s_mov_b32 s65, s56
	s_mov_b32 s66, s56
	s_mov_b32 s67, s56
	s_mov_b32 s68, s56
	s_mov_b32 s69, s56
	s_mov_b32 s70, s56
	s_mov_b32 s71, s56
	s_movk_i32 s23, 0x71
	v_lshlrev_b32_sdwa v112, v201, v31 dst_sel:DWORD dst_unused:UNUSED_PAD src0_sel:DWORD src1_sel:BYTE_0
	v_lshl_add_u64 v[114:115], v[22:23], 0, v[24:25]
	v_lshl_add_u64 v[116:117], v[20:21], 0, v[26:27]
	v_lshlrev_b32_e32 v141, 2, v33
	v_sub_u32_sdwa v143, s23, v30 dst_sel:DWORD dst_unused:UNUSED_PAD src0_sel:DWORD src1_sel:WORD_0
	v_sub_u32_e32 v142, v32, v141
	v_mov_b32_e32 v144, 0
	v_mov_b32_e32 v145, 0xff800000
	s_waitcnt vmcnt(19)
	v_mfma_f32_32x32x16_bf16 v[48:63], v[0:3], v[64:67], 0
	s_waitcnt vmcnt(17)
	v_mfma_f32_32x32x16_bf16 v[48:63], v[4:7], v[68:71], v[48:63]
	s_waitcnt vmcnt(15)
	v_mfma_f32_32x32x16_bf16 v[48:63], v[8:11], v[72:75], v[48:63]
	v_mov_b64_e32 v[0:1], s[56:57]
	v_mov_b64_e32 v[14:15], s[70:71]
	v_mov_b64_e32 v[2:3], s[58:59]
	v_mov_b64_e32 v[4:5], s[60:61]
	v_mov_b64_e32 v[6:7], s[62:63]
	v_mov_b64_e32 v[8:9], s[64:65]
	v_mov_b64_e32 v[10:11], s[66:67]
	s_waitcnt vmcnt(12)
	v_mfma_f32_32x32x16_bf16 v[48:63], v[16:19], v[76:79], v[48:63]
	v_mov_b64_e32 v[12:13], s[68:69]
	v_mov_b64_e32 v[30:31], v[14:15]
	v_mov_b64_e32 v[28:29], v[12:13]
	v_mov_b64_e32 v[26:27], v[10:11]
	v_mov_b64_e32 v[24:25], v[8:9]
	v_mov_b64_e32 v[22:23], v[6:7]
	v_mov_b64_e32 v[20:21], v[4:5]
	v_mov_b64_e32 v[18:19], v[2:3]
	v_mov_b64_e32 v[16:17], v[0:1]
	s_branch .LBB0_1034
